# group-barrier acquire: L1-only invalidate (buffer_inv sc0) when the barrier instance sits on one XCC (nx<2, read from the LDS state), agent-scope invalidate kept for nx>=2
# speedup vs baseline: 1.0427x; 1.0363x over previous
; DI unsigned xb_ld(unsigned* p)              { return __hip_atomic_load(p, __ATOMIC_RELAXED, __HIP_MEMORY_SCOPE_AGENT); }
; DI unsigned xb_add(unsigned* p, unsigned v) { return __hip_atomic_fetch_add(p, v, __ATOMIC_RELAXED, __HIP_MEMORY_SCOPE_AGENT); }
; #define XB_SPIN(cond, bar) do { unsigned _sp = 0; while (cond) { __builtin_amdgcn_s_sleep(1); \
;     if ((++_sp & 255u) == 0u) { if (xb_ld(&(bar)[XB_TMO])) break; if (_sp > XB_SPIN_CAP) { atomicAdd(&(bar)[XB_TMO], 1u); break; } } } } while (0)
; DI void xcd_barrier(const XcdBarrier& b) {
;     ...
;             if (nx > 1u) {
;               __builtin_amdgcn_fence(__ATOMIC_RELEASE, "agent");
;               asm volatile("s_waitcnt vmcnt(0)" ::: "memory");
;               const unsigned og = xb_add(&bar[XB_TOP], 1u);
;               const unsigned tg = og / nx;
;               if (og + 1u == (tg + 1u) * nx) xb_add(&bar[XB_TOPGEN], 1u);
;               else XB_SPIN(xb_ld(&bar[XB_TOPGEN]) == tg, bar);
;             }
;             __builtin_amdgcn_fence(__ATOMIC_ACQUIRE, "agent");
;             xb_add(&bar[XB_XGEN(b.x)], 1u);
;             asm volatile("s_waitcnt vmcnt(0)" ::: "memory");
.LBB0_158:
	v_readlane_b32 s2, v234, 7
	v_readlane_b32 s3, v234, 8
	s_waitcnt vmcnt(0)
	v_readlane_b32 s6, v235, 22
	s_nop 1
	v_mov_b32_e32 v0, s6
	ds_read_b32 v0, v0 offset:4
	s_waitcnt lgkmcnt(0)
	v_cmp_gt_u32_e32 vcc, 2, v0
	s_cbranch_vccnz .Lxg_l1only_10
	buffer_inv sc1
	s_branch .Lxg_invdone_10
.Lxg_l1only_10:
	buffer_inv sc0
.Lxg_invdone_10:
	s_nop 2
	global_atomic_add v179, v188, s[2:3]
	s_waitcnt vmcnt(0)

; DI unsigned xb_ld(unsigned* p)              { return __hip_atomic_load(p, __ATOMIC_RELAXED, __HIP_MEMORY_SCOPE_AGENT); }
; #define XB_SPIN(cond, bar) do { unsigned _sp = 0; while (cond) { __builtin_amdgcn_s_sleep(1); \
;     if ((++_sp & 255u) == 0u) { if (xb_ld(&(bar)[XB_TMO])) break; if (_sp > XB_SPIN_CAP) { atomicAdd(&(bar)[XB_TMO], 1u); break; } } } } while (0)
; DI void xcd_barrier(const XcdBarrier& b) {
;     ...
;         } else {
;             XB_SPIN(xb_ld(&bar[XB_XGEN(b.x)]) == gen, bar);
;             __builtin_amdgcn_fence(__ATOMIC_ACQUIRE, "agent");
;             asm volatile("s_waitcnt vmcnt(0)" ::: "memory");
;         }
.LBB0_194:
	s_or_b64 exec, exec, s[4:5]
	s_waitcnt vmcnt(0)
	v_readlane_b32 s6, v235, 22
	s_nop 1
	v_mov_b32_e32 v0, s6
	ds_read_b32 v0, v0 offset:4
	s_waitcnt lgkmcnt(0)
	v_cmp_gt_u32_e32 vcc, 2, v0
	s_cbranch_vccnz .Lxg_l1only_1
	buffer_inv sc1
	s_branch .Lxg_invdone_1

; DI unsigned xb_ld(unsigned* p)              { return __hip_atomic_load(p, __ATOMIC_RELAXED, __HIP_MEMORY_SCOPE_AGENT); }
; DI unsigned xb_add(unsigned* p, unsigned v) { return __hip_atomic_fetch_add(p, v, __ATOMIC_RELAXED, __HIP_MEMORY_SCOPE_AGENT); }
; #define XB_SPIN(cond, bar) do { unsigned _sp = 0; while (cond) { __builtin_amdgcn_s_sleep(1); \
;     if ((++_sp & 255u) == 0u) { if (xb_ld(&(bar)[XB_TMO])) break; if (_sp > XB_SPIN_CAP) { atomicAdd(&(bar)[XB_TMO], 1u); break; } } } } while (0)
; DI void xcd_barrier(const XcdBarrier& b) {
;     ...
;         const unsigned old = xb_add(&bar[XB_XSUB(b.x)], 1u);
;         const unsigned gen = old / nloc;
;         if (old + 1u == (gen + 1u) * nloc) {
;             if (nx > 1u) {
;               __builtin_amdgcn_fence(__ATOMIC_RELEASE, "agent");
;               asm volatile("s_waitcnt vmcnt(0)" ::: "memory");
;               const unsigned og = xb_add(&bar[XB_TOP], 1u);
;               const unsigned tg = og / nx;
;               if (og + 1u == (tg + 1u) * nx) xb_add(&bar[XB_TOPGEN], 1u);
;               else XB_SPIN(xb_ld(&bar[XB_TOPGEN]) == tg, bar);
.Lxg_invdone_1:
	s_waitcnt vmcnt(0)
.LBB0_195:
	s_andn2_saveexec_b64 s[2:3], s[2:3]
	s_cbranch_execz .LBB0_213
	s_waitcnt lgkmcnt(0)
	v_cmp_gt_u32_e32 vcc, 2, v1
	s_cbranch_vccnz .LBB0_212
	v_readlane_b32 s2, v234, 9
	buffer_wbl2 sc1
	s_waitcnt vmcnt(0)
	v_readlane_b32 s3, v234, 10
	v_cvt_f32_u32_e32 v2, v1
	v_sub_u32_e32 v3, 0, v1
	s_mov_b64 s[4:5], -1
	v_rcp_iflag_f32_e32 v2, v2
	s_nop 0
	global_atomic_add v0, v179, v188, s[2:3] sc0
	v_readlane_b32 s2, v234, 11
	v_readlane_b32 s3, v234, 12
	v_mul_f32_e32 v2, 0x4f7ffffe, v2
	v_cvt_u32_f32_e32 v2, v2
	v_mul_lo_u32 v3, v3, v2
	v_mul_hi_u32 v3, v2, v3
	v_add_u32_e32 v2, v2, v3
	s_waitcnt vmcnt(0)
	v_mul_hi_u32 v2, v0, v2
	v_mul_lo_u32 v3, v2, v1
	v_sub_u32_e32 v3, v0, v3
	v_cmp_ge_u32_e32 vcc, v3, v1
	v_add_u32_e32 v4, 1, v2
	v_add_u32_e32 v0, 1, v0
	v_cndmask_b32_e32 v2, v2, v4, vcc
	v_sub_u32_e32 v4, v3, v1
	v_cndmask_b32_e32 v3, v3, v4, vcc
	v_cmp_ge_u32_e32 vcc, v3, v1
	v_add_u32_e32 v3, 1, v2
	s_nop 0
	v_cndmask_b32_e32 v2, v2, v3, vcc
	v_mul_lo_u32 v3, v1, v2
	v_add_u32_e32 v1, v3, v1
	v_cmp_ne_u32_e32 vcc, v0, v1
	v_mov_b64_e32 v[0:1], s[2:3]
	s_and_saveexec_b64 s[2:3], vcc
	s_cbranch_execz .LBB0_209
	v_readlane_b32 s4, v234, 11
	v_readlane_b32 s5, v234, 12
	s_mov_b64 s[6:7], 0
	s_nop 3
	global_load_dword v0, v179, s[4:5] sc1
	s_waitcnt vmcnt(0)
	v_cmp_eq_u32_e32 vcc, v0, v2
	s_and_saveexec_b64 s[4:5], vcc
	s_cbranch_execz .LBB0_208
	s_mov_b32 s16, 1
	s_branch .LBB0_201

; DI unsigned xb_ld(unsigned* p)              { return __hip_atomic_load(p, __ATOMIC_RELAXED, __HIP_MEMORY_SCOPE_AGENT); }
; DI unsigned xb_add(unsigned* p, unsigned v) { return __hip_atomic_fetch_add(p, v, __ATOMIC_RELAXED, __HIP_MEMORY_SCOPE_AGENT); }
; #define XB_SPIN(cond, bar) do { unsigned _sp = 0; while (cond) { __builtin_amdgcn_s_sleep(1); \
;     if ((++_sp & 255u) == 0u) { if (xb_ld(&(bar)[XB_TMO])) break; if (_sp > XB_SPIN_CAP) { atomicAdd(&(bar)[XB_TMO], 1u); break; } } } } while (0)
; DI void xcd_barrier(const XcdBarrier& b) {
;     ...
;         const unsigned old = xb_add(&bar[XB_XSUB(b.x)], 1u);
;         const unsigned gen = old / nloc;
;         if (old + 1u == (gen + 1u) * nloc) {
;             if (nx > 1u) {
;               __builtin_amdgcn_fence(__ATOMIC_RELEASE, "agent");
;               asm volatile("s_waitcnt vmcnt(0)" ::: "memory");
;               const unsigned og = xb_add(&bar[XB_TOP], 1u);
;               const unsigned tg = og / nx;
;               if (og + 1u == (tg + 1u) * nx) xb_add(&bar[XB_TOPGEN], 1u);
;               else XB_SPIN(xb_ld(&bar[XB_TOPGEN]) == tg, bar);
.Lxg_invdone_3:
	s_waitcnt vmcnt(0)
.LBB0_325:
	s_andn2_saveexec_b64 s[2:3], s[2:3]
	s_cbranch_execz .LBB0_343
	s_waitcnt lgkmcnt(0)
	v_cmp_gt_u32_e32 vcc, 2, v1
	s_cbranch_vccnz .LBB0_342
	v_readlane_b32 s2, v234, 9
	buffer_wbl2 sc1
	s_waitcnt vmcnt(0)
	v_readlane_b32 s3, v234, 10
	v_cvt_f32_u32_e32 v2, v1
	v_sub_u32_e32 v3, 0, v1
	s_mov_b64 s[4:5], -1
	v_rcp_iflag_f32_e32 v2, v2
	s_nop 0
	global_atomic_add v0, v179, v188, s[2:3] sc0
	v_readlane_b32 s2, v234, 11
	v_readlane_b32 s3, v234, 12
	v_mul_f32_e32 v2, 0x4f7ffffe, v2
	v_cvt_u32_f32_e32 v2, v2
	v_mul_lo_u32 v3, v3, v2
	v_mul_hi_u32 v3, v2, v3
	v_add_u32_e32 v2, v2, v3
	s_waitcnt vmcnt(0)
	v_mul_hi_u32 v2, v0, v2
	v_mul_lo_u32 v3, v2, v1
	v_sub_u32_e32 v3, v0, v3
	v_cmp_ge_u32_e32 vcc, v3, v1
	v_add_u32_e32 v4, 1, v2
	v_add_u32_e32 v0, 1, v0
	v_cndmask_b32_e32 v2, v2, v4, vcc
	v_sub_u32_e32 v4, v3, v1
	v_cndmask_b32_e32 v3, v3, v4, vcc
	v_cmp_ge_u32_e32 vcc, v3, v1
	v_add_u32_e32 v3, 1, v2
	s_nop 0
	v_cndmask_b32_e32 v2, v2, v3, vcc
	v_mul_lo_u32 v3, v1, v2
	v_add_u32_e32 v1, v3, v1
	v_cmp_ne_u32_e32 vcc, v0, v1
	v_mov_b64_e32 v[0:1], s[2:3]
	s_and_saveexec_b64 s[2:3], vcc
	s_cbranch_execz .LBB0_339
	v_readlane_b32 s4, v234, 11
	v_readlane_b32 s5, v234, 12
	s_mov_b64 s[6:7], 0
	s_nop 3
	global_load_dword v0, v179, s[4:5] sc1
	s_waitcnt vmcnt(0)
	v_cmp_eq_u32_e32 vcc, v0, v2
	s_and_saveexec_b64 s[4:5], vcc
	s_cbranch_execz .LBB0_338
	s_mov_b32 s16, 1
	s_branch .LBB0_331

; DI unsigned xb_ld(unsigned* p)              { return __hip_atomic_load(p, __ATOMIC_RELAXED, __HIP_MEMORY_SCOPE_AGENT); }
; DI unsigned xb_add(unsigned* p, unsigned v) { return __hip_atomic_fetch_add(p, v, __ATOMIC_RELAXED, __HIP_MEMORY_SCOPE_AGENT); }
; #define XB_SPIN(cond, bar) do { unsigned _sp = 0; while (cond) { __builtin_amdgcn_s_sleep(1); \
;     if ((++_sp & 255u) == 0u) { if (xb_ld(&(bar)[XB_TMO])) break; if (_sp > XB_SPIN_CAP) { atomicAdd(&(bar)[XB_TMO], 1u); break; } } } } while (0)
; DI void xcd_barrier(const XcdBarrier& b) {
;     ...
;         const unsigned old = xb_add(&bar[XB_XSUB(b.x)], 1u);
;         const unsigned gen = old / nloc;
;         if (old + 1u == (gen + 1u) * nloc) {
;             if (nx > 1u) {
;               __builtin_amdgcn_fence(__ATOMIC_RELEASE, "agent");
;               asm volatile("s_waitcnt vmcnt(0)" ::: "memory");
;               const unsigned og = xb_add(&bar[XB_TOP], 1u);
;               const unsigned tg = og / nx;
;               if (og + 1u == (tg + 1u) * nx) xb_add(&bar[XB_TOPGEN], 1u);
;               else XB_SPIN(xb_ld(&bar[XB_TOPGEN]) == tg, bar);
.Lxg_invdone_5:
	s_waitcnt vmcnt(0)
.LBB0_513:
	s_andn2_saveexec_b64 s[2:3], s[2:3]
	s_cbranch_execz .LBB0_531
	s_waitcnt lgkmcnt(0)
	v_cmp_gt_u32_e32 vcc, 2, v1
	s_cbranch_vccnz .LBB0_530
	v_readlane_b32 s2, v234, 9
	buffer_wbl2 sc1
	s_waitcnt vmcnt(0)
	v_readlane_b32 s3, v234, 10
	v_cvt_f32_u32_e32 v2, v1
	v_sub_u32_e32 v3, 0, v1
	s_mov_b64 s[4:5], -1
	v_rcp_iflag_f32_e32 v2, v2
	s_nop 0
	global_atomic_add v0, v179, v188, s[2:3] sc0
	v_readlane_b32 s2, v234, 11
	v_readlane_b32 s3, v234, 12
	v_mul_f32_e32 v2, 0x4f7ffffe, v2
	v_cvt_u32_f32_e32 v2, v2
	v_mul_lo_u32 v3, v3, v2
	v_mul_hi_u32 v3, v2, v3
	v_add_u32_e32 v2, v2, v3
	s_waitcnt vmcnt(0)
	v_mul_hi_u32 v2, v0, v2
	v_mul_lo_u32 v3, v2, v1
	v_sub_u32_e32 v3, v0, v3
	v_cmp_ge_u32_e32 vcc, v3, v1
	v_add_u32_e32 v4, 1, v2
	v_add_u32_e32 v0, 1, v0
	v_cndmask_b32_e32 v2, v2, v4, vcc
	v_sub_u32_e32 v4, v3, v1
	v_cndmask_b32_e32 v3, v3, v4, vcc
	v_cmp_ge_u32_e32 vcc, v3, v1
	v_add_u32_e32 v3, 1, v2
	s_nop 0
	v_cndmask_b32_e32 v2, v2, v3, vcc
	v_mul_lo_u32 v3, v1, v2
	v_add_u32_e32 v1, v3, v1
	v_cmp_ne_u32_e32 vcc, v0, v1
	v_mov_b64_e32 v[0:1], s[2:3]
	s_and_saveexec_b64 s[2:3], vcc
	s_cbranch_execz .LBB0_527
	v_readlane_b32 s4, v234, 11
	v_readlane_b32 s5, v234, 12
	s_mov_b64 s[6:7], 0
	s_nop 3
	global_load_dword v0, v179, s[4:5] sc1
	s_waitcnt vmcnt(0)
	v_cmp_eq_u32_e32 vcc, v0, v2
	s_and_saveexec_b64 s[4:5], vcc
	s_cbranch_execz .LBB0_526
	s_mov_b32 s16, 1
	s_branch .LBB0_519

; DI unsigned xb_ld(unsigned* p)              { return __hip_atomic_load(p, __ATOMIC_RELAXED, __HIP_MEMORY_SCOPE_AGENT); }
; DI unsigned xb_add(unsigned* p, unsigned v) { return __hip_atomic_fetch_add(p, v, __ATOMIC_RELAXED, __HIP_MEMORY_SCOPE_AGENT); }
; #define XB_SPIN(cond, bar) do { unsigned _sp = 0; while (cond) { __builtin_amdgcn_s_sleep(1); \
;     if ((++_sp & 255u) == 0u) { if (xb_ld(&(bar)[XB_TMO])) break; if (_sp > XB_SPIN_CAP) { atomicAdd(&(bar)[XB_TMO], 1u); break; } } } } while (0)
; DI void xcd_barrier(const XcdBarrier& b) {
;     ...
;         const unsigned old = xb_add(&bar[XB_XSUB(b.x)], 1u);
;         const unsigned gen = old / nloc;
;         if (old + 1u == (gen + 1u) * nloc) {
;             if (nx > 1u) {
;               __builtin_amdgcn_fence(__ATOMIC_RELEASE, "agent");
;               asm volatile("s_waitcnt vmcnt(0)" ::: "memory");
;               const unsigned og = xb_add(&bar[XB_TOP], 1u);
;               const unsigned tg = og / nx;
;               if (og + 1u == (tg + 1u) * nx) xb_add(&bar[XB_TOPGEN], 1u);
;               else XB_SPIN(xb_ld(&bar[XB_TOPGEN]) == tg, bar);
.Lxg_invdone_7:
	s_waitcnt vmcnt(0)
.LBB0_569:
	s_andn2_saveexec_b64 s[2:3], s[2:3]
	s_cbranch_execz .LBB0_587
	s_waitcnt lgkmcnt(0)
	v_cmp_gt_u32_e32 vcc, 2, v1
	s_cbranch_vccnz .LBB0_586
	v_readlane_b32 s2, v234, 9
	buffer_wbl2 sc1
	s_waitcnt vmcnt(0)
	v_readlane_b32 s3, v234, 10
	v_cvt_f32_u32_e32 v2, v1
	v_sub_u32_e32 v3, 0, v1
	s_mov_b64 s[4:5], -1
	v_rcp_iflag_f32_e32 v2, v2
	s_nop 0
	global_atomic_add v0, v179, v188, s[2:3] sc0
	v_readlane_b32 s2, v234, 11
	v_readlane_b32 s3, v234, 12
	v_mul_f32_e32 v2, 0x4f7ffffe, v2
	v_cvt_u32_f32_e32 v2, v2
	v_mul_lo_u32 v3, v3, v2
	v_mul_hi_u32 v3, v2, v3
	v_add_u32_e32 v2, v2, v3
	s_waitcnt vmcnt(0)
	v_mul_hi_u32 v2, v0, v2
	v_mul_lo_u32 v3, v2, v1
	v_sub_u32_e32 v3, v0, v3
	v_cmp_ge_u32_e32 vcc, v3, v1
	v_add_u32_e32 v4, 1, v2
	v_add_u32_e32 v0, 1, v0
	v_cndmask_b32_e32 v2, v2, v4, vcc
	v_sub_u32_e32 v4, v3, v1
	v_cndmask_b32_e32 v3, v3, v4, vcc
	v_cmp_ge_u32_e32 vcc, v3, v1
	v_add_u32_e32 v3, 1, v2
	s_nop 0
	v_cndmask_b32_e32 v2, v2, v3, vcc
	v_mul_lo_u32 v3, v1, v2
	v_add_u32_e32 v1, v3, v1
	v_cmp_ne_u32_e32 vcc, v0, v1
	v_mov_b64_e32 v[0:1], s[2:3]
	s_and_saveexec_b64 s[2:3], vcc
	s_cbranch_execz .LBB0_583
	v_readlane_b32 s4, v234, 11
	v_readlane_b32 s5, v234, 12
	s_mov_b64 s[6:7], 0
	s_nop 3
	global_load_dword v0, v179, s[4:5] sc1
	s_waitcnt vmcnt(0)
	v_cmp_eq_u32_e32 vcc, v0, v2
	s_and_saveexec_b64 s[4:5], vcc
	s_cbranch_execz .LBB0_582
	s_mov_b32 s16, 1
	s_branch .LBB0_575

; DI unsigned xb_ld(unsigned* p)              { return __hip_atomic_load(p, __ATOMIC_RELAXED, __HIP_MEMORY_SCOPE_AGENT); }
; DI unsigned xb_add(unsigned* p, unsigned v) { return __hip_atomic_fetch_add(p, v, __ATOMIC_RELAXED, __HIP_MEMORY_SCOPE_AGENT); }
; #define XB_SPIN(cond, bar) do { unsigned _sp = 0; while (cond) { __builtin_amdgcn_s_sleep(1); \
;     if ((++_sp & 255u) == 0u) { if (xb_ld(&(bar)[XB_TMO])) break; if (_sp > XB_SPIN_CAP) { atomicAdd(&(bar)[XB_TMO], 1u); break; } } } } while (0)
; DI void xcd_barrier(const XcdBarrier& b) {
;     ...
;         const unsigned old = xb_add(&bar[XB_XSUB(b.x)], 1u);
;         const unsigned gen = old / nloc;
;         if (old + 1u == (gen + 1u) * nloc) {
;             if (nx > 1u) {
;               __builtin_amdgcn_fence(__ATOMIC_RELEASE, "agent");
;               asm volatile("s_waitcnt vmcnt(0)" ::: "memory");
;               const unsigned og = xb_add(&bar[XB_TOP], 1u);
;               const unsigned tg = og / nx;
;               if (og + 1u == (tg + 1u) * nx) xb_add(&bar[XB_TOPGEN], 1u);
;               else XB_SPIN(xb_ld(&bar[XB_TOPGEN]) == tg, bar);
.Lxg_invdone_9:
	s_waitcnt vmcnt(0)
.LBB0_660:
	s_andn2_saveexec_b64 s[2:3], s[2:3]
	s_cbranch_execz .LBB0_159
	s_waitcnt lgkmcnt(0)
	v_cmp_gt_u32_e32 vcc, 2, v1
	s_cbranch_vccnz .LBB0_158
	v_readlane_b32 s2, v234, 9
	buffer_wbl2 sc1
	s_waitcnt vmcnt(0)
	v_readlane_b32 s3, v234, 10
	v_cvt_f32_u32_e32 v2, v1
	v_sub_u32_e32 v3, 0, v1
	s_mov_b64 s[4:5], -1
	v_rcp_iflag_f32_e32 v2, v2
	s_nop 0
	global_atomic_add v0, v179, v188, s[2:3] sc0
	v_readlane_b32 s2, v234, 11
	v_readlane_b32 s3, v234, 12
	v_mul_f32_e32 v2, 0x4f7ffffe, v2
	v_cvt_u32_f32_e32 v2, v2
	v_mul_lo_u32 v3, v3, v2
	v_mul_hi_u32 v3, v2, v3
	v_add_u32_e32 v2, v2, v3
	s_waitcnt vmcnt(0)
	v_mul_hi_u32 v2, v0, v2
	v_mul_lo_u32 v3, v2, v1
	v_sub_u32_e32 v3, v0, v3
	v_cmp_ge_u32_e32 vcc, v3, v1
	v_add_u32_e32 v4, 1, v2
	v_add_u32_e32 v0, 1, v0
	v_cndmask_b32_e32 v2, v2, v4, vcc
	v_sub_u32_e32 v4, v3, v1
	v_cndmask_b32_e32 v3, v3, v4, vcc
	v_cmp_ge_u32_e32 vcc, v3, v1
	v_add_u32_e32 v3, 1, v2
	s_nop 0
	v_cndmask_b32_e32 v2, v2, v3, vcc
	v_mul_lo_u32 v3, v1, v2
	v_add_u32_e32 v1, v3, v1
	v_cmp_ne_u32_e32 vcc, v0, v1
	v_mov_b64_e32 v[0:1], s[2:3]
	s_and_saveexec_b64 s[2:3], vcc
	s_cbranch_execz .LBB0_674
	v_readlane_b32 s4, v234, 11
	v_readlane_b32 s5, v234, 12
	s_mov_b64 s[6:7], 0
	s_nop 3
	global_load_dword v0, v179, s[4:5] sc1
	s_waitcnt vmcnt(0)
	v_cmp_eq_u32_e32 vcc, v0, v2
	s_and_saveexec_b64 s[4:5], vcc
	s_cbranch_execz .LBB0_673
	s_mov_b32 s16, 1
	s_branch .LBB0_666
